# inproj workgroup stagger shortened to one sleep per group (about 2 us apart instead of 6 us)
# speedup vs baseline: 1.0270x; 1.0017x over previous
.LBB0_982:
	s_andn2_b64 vcc, exec, s[0:1]
	s_mov_b64 s[2:3], 0
	s_cbranch_vccnz .LBB0_1587
	v_readlane_b32 s0, v252, 61
	v_readlane_b32 s1, v252, 62
	s_lshl_b64 s[0:1], s[0:1], 22
	v_writelane_b32 v253, s0, 10
	s_nop 1
	v_writelane_b32 v253, s1, 11
	s_nop 0
	v_readlane_b32 s0, v253, 1
	s_cmp_gt_i32 s0, 0
	s_mov_b64 s[0:1], -1
	s_cbranch_scc0 .LBB0_1585
	v_readlane_b32 s4, v252, 61
	s_lshl_b32 s0, s4, 11
	s_ashr_i32 s1, s0, 31
	v_readlane_b32 s2, v253, 4
	v_readlane_b32 s5, v252, 62
	v_readlane_b32 s3, v253, 5
	s_add_u32 s64, s2, 0x3080000
	s_addc_u32 s65, s3, 0
	s_lshl_b64 s[2:3], s[4:5], 15
	s_add_u32 s66, s2, 0x35d2000
	s_addc_u32 s67, s3, 0
	v_readlane_b32 s2, v253, 10
	v_readlane_b32 s3, v253, 11
	s_add_u32 s68, s2, 0x2880000
	s_addc_u32 s69, s3, 0
	v_readlane_b32 s8, v253, 8
	v_readlane_b32 s9, v253, 9
	s_add_u32 s70, s8, 0x35b2000
	s_addc_u32 s71, s9, 0
	s_add_u32 s72, s2, 0x2080000
	s_addc_u32 s73, s3, 0
	s_add_u32 s74, s8, 0x3592000
	s_addc_u32 s75, s9, 0
	s_lshl_b64 s[0:1], s[0:1], 2
	v_readlane_b32 s16, v252, 38
	v_readlane_b32 s17, v252, 39
	v_readlane_b32 s18, v252, 40
	v_readlane_b32 s19, v252, 41
	v_readlane_b32 s20, v252, 42
	v_readlane_b32 s21, v252, 43
	v_readlane_b32 s22, v252, 44
	v_readlane_b32 s23, v252, 45
	v_readlane_b32 s24, v252, 46
	v_readlane_b32 s25, v252, 47
	v_readlane_b32 s26, v252, 48
	v_readlane_b32 s27, v252, 49
	v_readlane_b32 s28, v252, 50
	v_readlane_b32 s29, v252, 51
	v_readlane_b32 s30, v252, 52
	v_readlane_b32 s31, v252, 53
	s_add_u32 s10, s16, s0
	s_addc_u32 s11, s17, s1
	v_readlane_b32 s16, v251, 1
	v_readlane_b32 s30, v251, 15
	v_readlane_b32 s31, v251, 16
	s_mov_b64 s[12:13], s[30:31]
	s_add_u32 s76, s12, 0x1f80000
	v_readlane_b32 s18, v251, 3
	s_addc_u32 s77, s13, 0
	v_readlane_b32 s19, v251, 4
	s_add_u32 s18, s12, 0x12380000
	v_readlane_b32 s20, v251, 5
	s_addc_u32 s19, s13, 0
	v_readlane_b32 s21, v251, 6
	s_add_u32 s20, s12, 0xa180000
	v_readlane_b32 s22, v251, 7
	s_addc_u32 s21, s13, 0
	v_readlane_b32 s23, v251, 8
	s_add_u32 s22, s12, 0x22982200
	v_readlane_b32 s24, v251, 9
	s_addc_u32 s23, s13, 0
	v_readlane_b32 s25, v251, 10
	s_add_u32 s24, s12, 0x23d82200
	v_readlane_b32 s26, v251, 11
	s_addc_u32 s25, s13, 0
	v_readlane_b32 s27, v251, 12
	s_add_u32 s26, s12, 0x22182200
	v_readlane_b32 s17, v251, 2
	v_readlane_b32 s28, v251, 13
	v_readlane_b32 s29, v251, 14
	s_addc_u32 s27, s13, 0
	s_mov_b64 s[16:17], s[28:29]
	s_add_u32 s28, s12, 0x21982200
	s_addc_u32 s29, s13, 0
	s_mul_hi_i32 s0, s4, 0x90000
	s_mul_i32 s1, s4, 0x90000
	s_mul_hi_i32 s2, s4, 0x24000
	s_mul_i32 s3, s4, 0x24000
	v_mov_b32_e32 v0, v211
	v_readlane_b32 s4, v251, 21
	s_add_u32 s30, s12, 0x6080000
	v_readlane_b32 s5, v251, 22
	s_waitcnt vmcnt(0)
	v_lshrrev_b32_e32 v4, 2, v0
	s_addc_u32 s31, s13, 0
	s_load_dword s78, s[4:5], 0x0
	v_lshrrev_b32_e32 v3, 1, v0
	v_and_b32_e32 v4, 12, v4
	s_movk_i32 s4, 0x60
	s_add_u32 s3, s16, s3
	v_and_b32_e32 v2, 15, v0
	v_and_or_b32 v135, v3, s4, v4
	v_ashrrev_i32_e32 v0, 2, v0
	s_movk_i32 s4, 0xffc0
	s_addc_u32 s2, s17, s2
	v_and_or_b32 v150, v0, s4, v2
	s_add_u32 s34, s3, 0xd200000
	v_subrev_co_u32_e64 v134, s[4:5], 13, v2
	s_addc_u32 s35, s2, 0
	s_xor_b64 s[36:37], s[4:5], -1
	s_add_u32 s1, s16, s1
	s_addc_u32 s0, s17, s0
	s_add_u32 s38, s1, 0xd788000
	s_addc_u32 s39, s0, 0
	s_mov_b32 s79, 0
	v_readlane_b32 s0, v251, 0
	s_cmp_lt_u32 s0, 44
	s_cbranch_scc1 .Lstag_ip_done
	s_lshr_b32 s0, s0, 3
	s_and_b32 s0, s0, 3
	s_lshl_b32 s0, s0, 0
